# c_kv normalisation pre-pass: 4 rows' loads in flight at once; next-tile K fragment reads hoisted above last PV MFMAs (diff loops)
# speedup vs baseline: 1.0052x; 1.0052x over previous
.LBB0_132:
	s_and_b32 s5, s64, 7
	s_lshl_b32 s0, s5, 8
	s_or_b32 s22, s14, s0
	s_mov_b32 s23, s15
	s_lshl_b64 s[0:1], s[22:23], 10
	s_add_u32 s0, s55, s0
	s_addc_u32 s1, s56, s1
	s_lshl_b32 s4, s64, 4
	s_and_b32 s65, s4, 0x180
	s_lshl_b32 s4, s65, 1
	s_add_u32 s30, s0, s4
	s_addc_u32 s31, s1, 0
	s_lshl_b64 s[0:1], s[2:3], 21
	s_add_u32 s3, s57, s0
	s_addc_u32 s6, s58, s1
	s_add_u32 s24, s3, s4
	s_addc_u32 s25, s6, 0
	v_mov_b32_e32 v121, v218
	s_add_u32 s0, s90, s0
	v_mov_b32_e32 v4, v218
	s_addc_u32 s1, s91, s1
	s_add_u32 s3, s0, s4
	v_ashrrev_i32_e32 v0, 6, v4
	v_and_b32_e32 v6, 31, v4
	v_readfirstlane_b32 s0, v0
	v_lshl_or_b32 v0, v0, 5, v6
	v_ashrrev_i32_e32 v1, 31, v0
	v_lshlrev_b64 v[0:1], 10, v[0:1]
	v_lshrrev_b32_e32 v7, 1, v4
	v_and_b32_e32 v5, 63, v4
	v_lshl_add_u64 v[0:1], s[30:31], 0, v[0:1]
	v_and_b32_e32 v184, 16, v7
	s_addc_u32 s66, s1, 0
	v_lshl_add_u64 v[0:1], v[0:1], 0, v[184:185]
	s_lshl_b32 s1, s0, 10
	v_lshlrev_b32_e32 v8, 4, v5
	global_load_dwordx4 v[96:99], v[0:1], off
	global_load_dwordx4 v[100:103], v[0:1], off offset:32
	global_load_dwordx4 v[104:107], v[0:1], off offset:64
	global_load_dwordx4 v[108:111], v[0:1], off offset:96
	v_or_b32_e32 v0, s1, v8
	v_ashrrev_i32_e32 v1, 31, v0
	v_lshrrev_b32_e32 v1, 25, v1
	v_add_u32_e32 v1, v0, v1
	v_lshlrev_b32_e32 v9, 3, v5
	s_lshl_b32 s0, s0, 6
	v_ashrrev_i32_e32 v2, 7, v1
	v_and_b32_e32 v1, 0xffffff80, v1
	v_and_b32_e32 v3, 32, v4
	s_and_b32 s0, s0, 64
	v_and_b32_e32 v10, 24, v9
	v_sub_u32_e32 v0, v0, v1
	v_or3_b32 v3, v10, v3, s0
	s_ashr_i32 s0, s1, 8
	v_ashrrev_i32_e32 v0, 4, v0
	v_lshrrev_b32_e32 v1, 1, v2
	s_and_b32 s6, s0, 0x7ffff0
	s_lshr_b32 s0, s0, 1
	v_bitop3_b32 v0, v1, v0, 7 bitop3:0x6c
	v_bfe_u32 v1, v4, 2, 2
	s_and_b32 s0, s0, 4
	v_and_or_b32 v1, v7, 8, v1
	s_or_b32 s0, s6, s0
	v_or_b32_e32 v10, s0, v1
	s_add_i32 s0, s1, 0x2000
	s_ashr_i32 s0, s0, 8
	s_and_b32 s6, s0, 0x7ffff0
	s_lshr_b32 s0, s0, 1
	s_and_b32 s0, s0, 4
	s_or_b32 s0, s6, s0
	s_add_i32 s4, 0, 0x14000
	v_or_b32_e32 v1, s0, v1
	s_lshl_b32 s0, s5, 17
	s_lshl_b32 s6, s5, 18
	v_lshl_or_b32 v114, v1, 9, v3
	v_lshlrev_b32_e32 v1, 9, v2
	s_add_u32 s68, s24, s6
	v_lshl_add_u32 v0, v0, 3, v1
	s_addc_u32 s69, s25, 0
	s_add_i32 s5, s1, 0
	v_ashrrev_i32_e32 v1, 31, v0
	s_add_i32 m0, s5, 0x8000
	v_lshl_or_b32 v112, v10, 9, v3
	v_lshlrev_b64 v[0:1], 1, v[0:1]
	s_add_u32 s34, s3, s6
	v_lshl_add_u64 v[2:3], s[68:69], 0, v[0:1]
	s_addc_u32 s35, s66, 0
	v_ashrrev_i32_e32 v113, 31, v112
	s_waitcnt lgkmcnt(0)
	s_barrier
	global_load_lds_dwordx4 v[2:3], off
	v_lshl_add_u64 v[2:3], v[112:113], 1, s[34:35]
	s_mov_b32 m0, s5
	v_ashrrev_i32_e32 v115, 31, v114
	global_load_lds_dwordx4 v[2:3], off
	v_lshl_add_u64 v[2:3], v[114:115], 1, s[34:35]
	s_add_i32 m0, s5, 0x2000
	s_cmp_lg_u32 0, -1
	global_load_lds_dwordx4 v[2:3], off
	v_and_b32_e32 v2, 0x3fffffc0, v4
	v_lshl_add_u32 v119, v2, 2, s4
	v_lshlrev_b32_e32 v2, 1, v4
	s_cselect_b32 s1, 0, 0
	v_and_b32_e32 v2, 32, v2
	v_lshlrev_b32_e32 v4, 3, v4
	s_add_i32 s6, s1, 0x8000
	s_movk_i32 s54, 0x118
	v_and_b32_e32 v3, 0xc0, v8
	s_waitcnt vmcnt(0)
	v_and_b32_e32 v4, 0x70, v4
	v_lshl_add_u32 v120, v6, 7, s6
	s_movk_i32 s6, 0x60
	v_lshl_add_u64 v[116:117], s[24:25], 0, v[0:1]
	v_and_or_b32 v0, v9, s54, v2
	v_mov_b32_e32 v14, v185
	v_mov_b32_e32 v15, v185
	v_bitop3_b32 v123, v7, v4, 16 bitop3:0x6c
	v_bitop3_b32 v124, v184, v4, 32 bitop3:0x36
	v_bitop3_b32 v125, v184, v4, 64 bitop3:0x36
	v_bitop3_b32 v126, v184, v4, s6 bitop3:0x36
	v_cmp_gt_u32_e64 s[6:7], 32, v5
	v_lshl_add_u32 v122, v6, 2, v119
	v_add3_u32 v127, v3, s1, v0
	s_or_b32 s67, s0, 0x8000
	v_mov_b32_e32 v0, v185
	v_mov_b32_e32 v1, v185
	v_mov_b32_e32 v2, v185
	v_mov_b32_e32 v3, v185
	v_mov_b32_e32 v4, v185
	v_mov_b32_e32 v5, v185
	v_mov_b32_e32 v6, v185
	v_mov_b32_e32 v7, v185
	v_mov_b32_e32 v8, v185
	v_mov_b32_e32 v9, v185
	v_mov_b32_e32 v10, v185
	v_mov_b32_e32 v11, v185
	v_mov_b32_e32 v12, v185
	v_mov_b32_e32 v13, v185
	v_mov_b64_e32 v[30:31], v[14:15]
	v_mov_b64_e32 v[46:47], v[14:15]
	v_mov_b64_e32 v[62:63], v[14:15]
	s_mov_b32 s53, 0
	v_mov_b32_e32 v128, 0
	v_mov_b32_e32 v160, 0x80000000
	v_mov_b32_e32 v161, 0x80000000
	v_mov_b32_e32 v162, 0x80000000
	v_mov_b32_e32 v163, 0x80000000
	v_mov_b32_e32 v164, 0x80000000
	v_mov_b32_e32 v165, 0x80000000
	v_mov_b32_e32 v166, 0x80000000
	v_mov_b32_e32 v167, 0x80000000
	v_mov_b32_e32 v168, 0x80000000
	v_mov_b32_e32 v169, 0x80000000
	v_mov_b32_e32 v170, 0x80000000
	v_mov_b32_e32 v171, 0x80000000
	v_mov_b32_e32 v172, 0x80000000
	v_mov_b32_e32 v173, 0x80000000
	v_mov_b32_e32 v174, 0x80000000
	v_mov_b32_e32 v175, 0x80000000
	s_mov_b32 s54, s67
	v_mov_b64_e32 v[28:29], v[12:13]
	v_mov_b64_e32 v[26:27], v[10:11]
	v_mov_b64_e32 v[24:25], v[8:9]
	v_mov_b64_e32 v[22:23], v[6:7]
	v_mov_b64_e32 v[20:21], v[4:5]
	v_mov_b64_e32 v[18:19], v[2:3]
	v_mov_b64_e32 v[16:17], v[0:1]
	v_mov_b64_e32 v[44:45], v[12:13]
	v_mov_b64_e32 v[42:43], v[10:11]
	v_mov_b64_e32 v[40:41], v[8:9]
	v_mov_b64_e32 v[38:39], v[6:7]
	v_mov_b64_e32 v[36:37], v[4:5]
	v_mov_b64_e32 v[34:35], v[2:3]
	v_mov_b64_e32 v[32:33], v[0:1]
	v_mov_b64_e32 v[60:61], v[12:13]
	v_mov_b64_e32 v[58:59], v[10:11]
	v_mov_b64_e32 v[56:57], v[8:9]
	v_mov_b64_e32 v[54:55], v[6:7]
	v_mov_b64_e32 v[52:53], v[4:5]
	v_mov_b64_e32 v[50:51], v[2:3]
	v_mov_b64_e32 v[48:49], v[0:1]
	v_mov_b32_e32 v129, 0
	s_waitcnt vmcnt(0) lgkmcnt(0)
	s_barrier
	s_and_b32 s80, s53, 1
	v_add_u32_e32 v118, v120, v123
	ds_read_b128 v[130:133], v118 offset:0
	ds_read_b128 v[134:137], v118 offset:0x1000
	s_cmp_eq_u32 s53, 31
	s_movk_i32 s0, 0x2000
	s_cbranch_scc1 .LBB0_134

.LBB0_134:
	v_add_u32_e32 v80, s0, v120
	v_add_u32_e32 v82, v80, v124
	ds_read_b128 v[138:141], v82 offset:0
	ds_read_b128 v[146:149], v82 offset:0x1000
	s_waitcnt lgkmcnt(2)
	v_add_u32_e32 v118, v80, v125
	v_add_u32_e32 v142, v80, v126
	v_mfma_f32_32x32x16_bf16 v[80:95], v[130:133], v[96:99], v[160:175]
	ds_read_b128 v[130:133], v118 offset:0
	v_mfma_f32_32x32x16_bf16 v[64:79], v[134:137], v[96:99], v[160:175]
	ds_read_b128 v[134:137], v118 offset:0x1000
	s_waitcnt lgkmcnt(2)
	v_mfma_f32_32x32x16_bf16 v[80:95], v[138:141], v[100:103], v[80:95]
	ds_read_b128 v[138:141], v142 offset:0
	v_mfma_f32_32x32x16_bf16 v[64:79], v[146:149], v[100:103], v[64:79]
	ds_read_b128 v[146:149], v142 offset:0x1000
	s_waitcnt lgkmcnt(2)
	v_mfma_f32_32x32x16_bf16 v[80:95], v[130:133], v[104:107], v[80:95]
	s_waitcnt lgkmcnt(0)
	v_mfma_f32_32x32x16_bf16 v[64:79], v[134:137], v[104:107], v[64:79]
	v_mfma_f32_32x32x16_bf16 v[80:95], v[138:141], v[108:111], v[80:95]
	s_cmp_eq_u32 s53, 0
	s_cselect_b64 s[70:71], -1, 0
	s_cmp_lg_u32 s53, 0
	v_mfma_f32_32x32x16_bf16 v[64:79], v[146:149], v[108:111], v[64:79]
	s_nop 7
	v_max_f32_e32 v118, v80, v81
	v_max3_f32 v118, v118, v82, v83
	v_max3_f32 v118, v118, v84, v85
	v_max3_f32 v118, v118, v86, v87
	v_max3_f32 v118, v118, v88, v89
	v_max3_f32 v118, v118, v90, v91
	v_max3_f32 v118, v118, v92, v93
	v_max3_f32 v118, v118, v94, v95
	v_max3_f32 v118, v118, v64, v65
	v_max3_f32 v118, v118, v66, v67
	v_max3_f32 v118, v118, v68, v69
	v_max3_f32 v118, v118, v70, v71
	v_max3_f32 v118, v118, v72, v73
	v_max3_f32 v118, v118, v74, v75
	v_max3_f32 v118, v118, v76, v77
	v_max3_f32 v118, v118, v78, v79
	v_mov_b32_e32 v130, v118
	s_nop 1
	v_permlane32_swap_b32_e32 v118, v130
	v_max_f32_e32 v130, v118, v130
	s_cbranch_scc0 .LBB0_139
	v_cmp_ge_f32_e32 vcc, s62, v130
	s_cmp_lg_u64 vcc, exec
	s_mov_b64 s[74:75], 0
	s_mov_b64 s[72:73], 0
	s_cbranch_scc1 .LBB0_140
	v_mov_b32_e32 v130, 1.0
	s_branch .LBB0_146

.LBB0_146:
	v_exp_f32_e32 v80, v80
	v_exp_f32_e32 v81, v81
	v_exp_f32_e32 v82, v82
	v_exp_f32_e32 v83, v83
	v_exp_f32_e32 v84, v84
	v_exp_f32_e32 v118, v64
	v_add_f32_e32 v64, 0, v80
	v_exp_f32_e32 v85, v85
	v_add_f32_e32 v64, v81, v64
	v_exp_f32_e32 v86, v86
	v_add_f32_e32 v64, v82, v64
	v_exp_f32_e32 v87, v87
	v_add_f32_e32 v64, v83, v64
	v_exp_f32_e32 v88, v88
	v_add_f32_e32 v64, v84, v64
	v_exp_f32_e32 v89, v89
	v_add_f32_e32 v64, v85, v64
	v_exp_f32_e32 v90, v90
	v_add_f32_e32 v64, v86, v64
	v_exp_f32_e32 v91, v91
	v_add_f32_e32 v64, v87, v64
	v_exp_f32_e32 v92, v92
	v_add_f32_e32 v64, v88, v64
	v_exp_f32_e32 v93, v93
	v_add_f32_e32 v64, v89, v64
	v_exp_f32_e32 v94, v94
	v_add_f32_e32 v64, v90, v64
	v_exp_f32_e32 v95, v95
	v_add_f32_e32 v64, v91, v64
	v_add_f32_e32 v64, v92, v64
	v_exp_f32_e32 v65, v65
	v_add_f32_e32 v64, v93, v64
	v_exp_f32_e32 v131, v66
	v_add_f32_e32 v64, v94, v64
	v_exp_f32_e32 v132, v67
	v_add_f32_e32 v64, v95, v64
	v_exp_f32_e32 v133, v68
	v_add_f32_e32 v64, v118, v64
	v_exp_f32_e32 v134, v69
	v_add_f32_e32 v64, v65, v64
	v_exp_f32_e32 v135, v70
	v_add_f32_e32 v64, v131, v64
	v_exp_f32_e32 v136, v71
	v_add_f32_e32 v64, v132, v64
	v_exp_f32_e32 v137, v72
	v_add_f32_e32 v64, v133, v64
	v_exp_f32_e32 v138, v73
	v_add_f32_e32 v64, v134, v64
	v_exp_f32_e32 v139, v74
	v_add_f32_e32 v64, v135, v64
	v_exp_f32_e32 v140, v75
	v_add_f32_e32 v64, v136, v64
	v_exp_f32_e32 v141, v76
	v_add_f32_e32 v64, v137, v64
	v_exp_f32_e32 v142, v77
	v_add_f32_e32 v64, v138, v64
	v_exp_f32_e32 v143, v78
	v_add_f32_e32 v64, v139, v64
	v_exp_f32_e32 v146, v79
	v_add_f32_e32 v64, v140, v64
	v_add_f32_e32 v64, v141, v64
	v_add_f32_e32 v64, v142, v64
	v_add_f32_e32 v64, v143, v64
	v_add_f32_e32 v64, v146, v64
	v_mov_b32_e32 v66, v64
	s_nop 1
	v_permlane32_swap_b32_e32 v64, v66
	v_add_f32_e32 v64, v64, v66
	s_add_i32 s53, s53, 1
	v_fmac_f32_e32 v64, v129, v130
	v_cvt_pk_bf16_f32 v66, v80, v81
	v_cvt_pk_bf16_f32 v67, v82, v83
	v_cvt_pk_bf16_f32 v68, v84, v85
	v_cvt_pk_bf16_f32 v69, v86, v87
	v_cvt_pk_bf16_f32 v70, v88, v89
	v_cvt_pk_bf16_f32 v71, v90, v91
	v_cvt_pk_bf16_f32 v72, v92, v93
	v_cvt_pk_bf16_f32 v73, v94, v95
	v_cvt_pk_bf16_f32 v74, v118, v65
	v_cvt_pk_bf16_f32 v75, v131, v132
	v_cvt_pk_bf16_f32 v76, v133, v134
	v_cvt_pk_bf16_f32 v77, v135, v136
	v_cvt_pk_bf16_f32 v78, v137, v138
	v_cvt_pk_bf16_f32 v79, v139, v140
	v_cvt_pk_bf16_f32 v80, v141, v142
	v_cvt_pk_bf16_f32 v81, v143, v146
	s_nop 0
	v_permlane32_swap_b32_e32 v66, v68
	v_permlane32_swap_b32_e32 v67, v69
	v_permlane32_swap_b32_e32 v70, v72
	v_permlane32_swap_b32_e32 v71, v73
	v_permlane32_swap_b32_e32 v74, v76
	v_permlane32_swap_b32_e32 v75, v77
	v_permlane32_swap_b32_e32 v78, v80
	v_permlane32_swap_b32_e32 v79, v81
	v_lshl_add_u32 v65, s80, 14, v127
	ds_read_b64_tr_b16 v[82:83], v65 offset:0
	ds_read_b64_tr_b16 v[84:85], v65 offset:0x800
	ds_read_b64_tr_b16 v[86:87], v65 offset:0x1000
	ds_read_b64_tr_b16 v[88:89], v65 offset:0x1800
	ds_read_b64_tr_b16 v[90:91], v65 offset:0x2000
	ds_read_b64_tr_b16 v[92:93], v65 offset:0x2800
	ds_read_b64_tr_b16 v[130:131], v65 offset:0x3000
	ds_read_b64_tr_b16 v[132:133], v65 offset:0x3800
	ds_read_b64_tr_b16 v[134:135], v65 offset:0x200
	ds_read_b64_tr_b16 v[136:137], v65 offset:0xa00
	ds_read_b64_tr_b16 v[138:139], v65 offset:0x1200
	ds_read_b64_tr_b16 v[140:141], v65 offset:0x1a00
	ds_read_b64_tr_b16 v[146:147], v65 offset:0x2200
	ds_read_b64_tr_b16 v[148:149], v65 offset:0x2a00
	ds_read_b64_tr_b16 v[150:151], v65 offset:0x3200
	ds_read_b64_tr_b16 v[152:153], v65 offset:0x3a00
	s_waitcnt lgkmcnt(8)
	s_nop 0
	v_mfma_f32_32x32x16_bf16 v[48:63], v[66:69], v[82:85], v[48:63]
	ds_read_b64_tr_b16 v[82:83], v65 offset:0x400
	ds_read_b64_tr_b16 v[84:85], v65 offset:0xc00
	v_mfma_f32_32x32x16_bf16 v[48:63], v[70:73], v[86:89], v[48:63]
	ds_read_b64_tr_b16 v[86:87], v65 offset:0x1400
	ds_read_b64_tr_b16 v[88:89], v65 offset:0x1c00
	v_mfma_f32_32x32x16_bf16 v[48:63], v[74:77], v[90:93], v[48:63]
	ds_read_b64_tr_b16 v[90:91], v65 offset:0x2400
	ds_read_b64_tr_b16 v[92:93], v65 offset:0x2c00
	v_mfma_f32_32x32x16_bf16 v[48:63], v[78:81], v[130:133], v[48:63]
	ds_read_b64_tr_b16 v[130:131], v65 offset:0x3400
	ds_read_b64_tr_b16 v[132:133], v65 offset:0x3c00
	s_waitcnt lgkmcnt(8)
	v_mfma_f32_32x32x16_bf16 v[32:47], v[66:69], v[134:137], v[32:47]
	ds_read_b64_tr_b16 v[134:135], v65 offset:0x600
	ds_read_b64_tr_b16 v[136:137], v65 offset:0xe00
	v_mfma_f32_32x32x16_bf16 v[32:47], v[70:73], v[138:141], v[32:47]
	ds_read_b64_tr_b16 v[138:139], v65 offset:0x1600
	ds_read_b64_tr_b16 v[140:141], v65 offset:0x1e00
	v_mfma_f32_32x32x16_bf16 v[32:47], v[74:77], v[146:149], v[32:47]
	ds_read_b64_tr_b16 v[146:147], v65 offset:0x2600
	ds_read_b64_tr_b16 v[148:149], v65 offset:0x2e00
	v_mfma_f32_32x32x16_bf16 v[32:47], v[78:81], v[150:153], v[32:47]
	ds_read_b64_tr_b16 v[150:151], v65 offset:0x3600
	ds_read_b64_tr_b16 v[152:153], v65 offset:0x3e00
	s_waitcnt lgkmcnt(8)
	v_mfma_f32_32x32x16_bf16 v[16:31], v[66:69], v[82:85], v[16:31]
	s_waitcnt lgkmcnt(0)
	v_mfma_f32_32x32x16_bf16 v[16:31], v[70:73], v[86:89], v[16:31]
	v_mfma_f32_32x32x16_bf16 v[16:31], v[74:77], v[90:93], v[16:31]
	v_mfma_f32_32x32x16_bf16 v[16:31], v[78:81], v[130:133], v[16:31]
	v_mfma_f32_32x32x16_bf16 v[0:15], v[66:69], v[134:137], v[0:15]
	s_waitcnt vmcnt(0)
	s_add_i32 s54, s54, 0x8000
	s_cmp_eq_u32 s53, 32
	s_waitcnt vmcnt(0) lgkmcnt(0)
	s_barrier
	s_and_b32 s1, s53, 1
	s_lshl_b32 s1, s1, 13
	v_add3_u32 v118, v120, v123, s1
	ds_read_b128 v[130:133], v118 offset:0
	ds_read_b128 v[134:137], v118 offset:0x1000
	s_cmp_eq_u32 s53, 32
	v_mfma_f32_32x32x16_bf16 v[0:15], v[70:73], v[138:141], v[0:15]
	v_mfma_f32_32x32x16_bf16 v[0:15], v[74:77], v[146:149], v[0:15]
	v_mfma_f32_32x32x16_bf16 v[0:15], v[78:81], v[150:153], v[0:15]
	s_cbranch_scc1 .LBB0_148
	v_mov_b32_e32 v129, v64
	s_and_b32 s80, s53, 1
	s_cmp_eq_u32 s53, 31
	s_movk_i32 s0, 0x2000
	s_cbranch_scc0 .LBB0_133
	s_branch .LBB0_134
.LBB0_148:
	s_and_saveexec_b64 s[0:1], s[6:7]
	ds_write_b32 v122, v64
	s_or_b64 exec, exec, s[0:1]
	v_lshlrev_b32_e32 v64, 6, v121
	v_ashrrev_i32_e32 v65, 31, v64
	s_waitcnt lgkmcnt(0)
	v_add_u32_e32 v80, v119, v184
	v_lshl_add_u64 v[112:113], v[64:65], 2, s[12:13]
	ds_read_b128 v[64:67], v80
	ds_read_b128 v[68:71], v80 offset:32
	s_mov_b32 s5, 0
	v_mov_b32_e32 v130, 0
	v_mov_b32_e32 v131, 0
	s_waitcnt lgkmcnt(1)
	v_rcp_f32_e32 v72, v64
	v_rcp_f32_e32 v73, v65
	v_rcp_f32_e32 v74, v66
	v_rcp_f32_e32 v75, v67
	ds_read_b128 v[64:67], v80 offset:64
	s_waitcnt lgkmcnt(1)
	v_rcp_f32_e32 v68, v68
	v_rcp_f32_e32 v69, v69
	v_rcp_f32_e32 v70, v70
	v_rcp_f32_e32 v71, v71
	s_waitcnt lgkmcnt(0)
	v_rcp_f32_e32 v76, v64
	v_rcp_f32_e32 v77, v65
	v_rcp_f32_e32 v78, v66
	v_rcp_f32_e32 v79, v67
	ds_read_b128 v[64:67], v80 offset:96
	v_pk_mul_f32 v[48:49], v[48:49], v[72:73]
	v_pk_mul_f32 v[50:51], v[50:51], v[74:75]
	v_pk_mul_f32 v[32:33], v[32:33], v[72:73]
	v_pk_mul_f32 v[34:35], v[34:35], v[74:75]
	s_waitcnt lgkmcnt(0)
	v_rcp_f32_e32 v64, v64
	v_rcp_f32_e32 v65, v65
	v_rcp_f32_e32 v66, v66
	v_rcp_f32_e32 v67, v67
	v_pk_mul_f32 v[16:17], v[16:17], v[72:73]
	v_pk_mul_f32 v[18:19], v[18:19], v[74:75]
	v_pk_mul_f32 v[0:1], v[0:1], v[72:73]
	v_pk_mul_f32 v[2:3], v[2:3], v[74:75]
	flat_store_dwordx4 v[112:113], v[48:51]
	flat_store_dwordx4 v[112:113], v[32:35] offset:64
	flat_store_dwordx4 v[112:113], v[16:19] offset:128
	v_pk_mul_f32 v[48:49], v[52:53], v[68:69]
	v_pk_mul_f32 v[50:51], v[54:55], v[70:71]
	v_pk_mul_f32 v[32:33], v[36:37], v[68:69]
	v_pk_mul_f32 v[34:35], v[38:39], v[70:71]
	v_pk_mul_f32 v[16:17], v[20:21], v[68:69]
	v_pk_mul_f32 v[18:19], v[22:23], v[70:71]
	flat_store_dwordx4 v[112:113], v[0:3] offset:192
	flat_store_dwordx4 v[112:113], v[48:51] offset:16
	flat_store_dwordx4 v[112:113], v[32:35] offset:80
	v_pk_mul_f32 v[0:1], v[4:5], v[68:69]
	v_pk_mul_f32 v[2:3], v[6:7], v[70:71]
	v_pk_mul_f32 v[48:49], v[56:57], v[76:77]
	v_pk_mul_f32 v[50:51], v[58:59], v[78:79]
	v_pk_mul_f32 v[32:33], v[40:41], v[76:77]
	v_pk_mul_f32 v[34:35], v[42:43], v[78:79]
	flat_store_dwordx4 v[112:113], v[16:19] offset:144
	flat_store_dwordx4 v[112:113], v[0:3] offset:208
	flat_store_dwordx4 v[112:113], v[48:51] offset:32
	v_pk_mul_f32 v[16:17], v[24:25], v[76:77]
	v_pk_mul_f32 v[18:19], v[26:27], v[78:79]
	v_pk_mul_f32 v[0:1], v[8:9], v[76:77]
	v_pk_mul_f32 v[2:3], v[10:11], v[78:79]
	v_pk_mul_f32 v[48:49], v[60:61], v[64:65]
	v_pk_mul_f32 v[50:51], v[62:63], v[66:67]
	flat_store_dwordx4 v[112:113], v[32:35] offset:96
	flat_store_dwordx4 v[112:113], v[16:19] offset:160
	flat_store_dwordx4 v[112:113], v[0:3] offset:224
	v_pk_mul_f32 v[32:33], v[44:45], v[64:65]
	v_pk_mul_f32 v[34:35], v[46:47], v[66:67]
	v_pk_mul_f32 v[16:17], v[28:29], v[64:65]
	v_pk_mul_f32 v[18:19], v[30:31], v[66:67]
	v_pk_mul_f32 v[0:1], v[12:13], v[64:65]
	v_pk_mul_f32 v[2:3], v[14:15], v[66:67]
	v_mov_b32_e32 v4, v218
	flat_store_dwordx4 v[112:113], v[48:51] offset:48
	flat_store_dwordx4 v[112:113], v[32:35] offset:112
	flat_store_dwordx4 v[112:113], v[16:19] offset:176
	flat_store_dwordx4 v[112:113], v[0:3] offset:240
	v_mov_b32_e32 v14, v185
	v_and_b32_e32 v6, 31, v4
	v_and_b32_e32 v0, 0x3fffffc0, v4
	v_lshl_add_u32 v122, v0, 2, s4
	v_ashrrev_i32_e32 v0, 6, v4
	v_lshrrev_b32_e32 v7, 1, v4
	v_readfirstlane_b32 s0, v0
	v_lshl_or_b32 v0, v0, 5, v6
	v_ashrrev_i32_e32 v1, 31, v0
	v_lshlrev_b64 v[0:1], 10, v[0:1]
	v_and_b32_e32 v5, 63, v4
	v_lshl_add_u64 v[0:1], s[30:31], 0, v[0:1]
	v_and_b32_e32 v184, 16, v7
	v_lshl_add_u64 v[0:1], v[0:1], 0, v[184:185]
	s_lshl_b32 s1, s0, 10
	v_lshlrev_b32_e32 v8, 4, v5
	global_load_dwordx4 v[96:99], v[0:1], off offset:128
	global_load_dwordx4 v[100:103], v[0:1], off offset:160
	global_load_dwordx4 v[104:107], v[0:1], off offset:192
	global_load_dwordx4 v[108:111], v[0:1], off offset:224
	v_or_b32_e32 v0, s1, v8
	v_ashrrev_i32_e32 v1, 31, v0
	v_lshrrev_b32_e32 v1, 25, v1
	v_add_u32_e32 v1, v0, v1
	v_lshlrev_b32_e32 v9, 3, v5
	s_lshl_b32 s0, s0, 6
	v_ashrrev_i32_e32 v2, 7, v1
	v_and_b32_e32 v1, 0xffffff80, v1
	v_and_b32_e32 v3, 32, v4
	s_and_b32 s0, s0, 64
	v_and_b32_e32 v10, 24, v9
	v_sub_u32_e32 v0, v0, v1
	v_or3_b32 v3, v10, v3, s0
	s_ashr_i32 s0, s1, 8
	v_ashrrev_i32_e32 v0, 4, v0
	v_lshrrev_b32_e32 v1, 1, v2
	s_and_b32 s4, s0, 0x7ffff0
	s_lshr_b32 s0, s0, 1
	v_bitop3_b32 v0, v1, v0, 7 bitop3:0x6c
	v_bfe_u32 v1, v4, 2, 2
	s_and_b32 s0, s0, 4
	v_and_or_b32 v1, v7, 8, v1
	s_or_b32 s0, s4, s0
	v_or_b32_e32 v10, s0, v1
	s_add_i32 s0, s1, 0x2000
	s_ashr_i32 s0, s0, 8
	s_and_b32 s4, s0, 0x7ffff0
	s_lshr_b32 s0, s0, 1
	s_and_b32 s0, s0, 4
	s_or_b32 s0, s4, s0
	v_or_b32_e32 v1, s0, v1
	v_lshl_or_b32 v116, v1, 9, v3
	v_lshlrev_b32_e32 v1, 9, v2
	v_lshl_add_u32 v0, v0, 3, v1
	v_ashrrev_i32_e32 v1, 31, v0
	v_lshlrev_b64 v[0:1], 1, v[0:1]
	v_lshl_or_b32 v114, v10, 9, v3
	v_lshl_add_u64 v[2:3], s[68:69], 0, v[0:1]
	s_add_i32 s4, s1, 0
	v_lshl_add_u64 v[2:3], v[2:3], 0, s[78:79]
	s_add_i32 m0, s4, 0x8000
	v_ashrrev_i32_e32 v115, 31, v114
	s_waitcnt lgkmcnt(0)
	s_barrier
	global_load_lds_dwordx4 v[2:3], off
	v_lshl_add_u64 v[2:3], v[114:115], 1, s[34:35]
	s_mov_b32 m0, s4
	v_ashrrev_i32_e32 v117, 31, v116
	global_load_lds_dwordx4 v[2:3], off
	v_lshl_add_u64 v[2:3], v[116:117], 1, s[34:35]
	s_add_i32 m0, s4, 0x2000
	s_cmp_lg_u32 0, -1
	global_load_lds_dwordx4 v[2:3], off
	s_cselect_b32 s0, 0, 0
	v_lshlrev_b32_e32 v10, 1, v4
	v_lshlrev_b32_e32 v4, 3, v4
	s_add_i32 s1, s0, 0x8000
	v_and_b32_e32 v4, 0x70, v4
	v_lshl_add_u32 v124, v6, 7, s1
	s_movk_i32 s1, 0x60
	v_and_b32_e32 v3, 32, v10
	v_bitop3_b32 v128, v184, v4, s1 bitop3:0x36
	s_movk_i32 s1, 0x118
	v_and_b32_e32 v2, 0xc0, v8
	s_waitcnt vmcnt(0)
	v_lshl_add_u64 v[118:119], s[24:25], 0, v[0:1]
	v_and_or_b32 v0, v9, s1, v3
	v_mov_b32_e32 v15, v185
	v_bitop3_b32 v125, v7, v4, 16 bitop3:0x6c
	v_bitop3_b32 v126, v184, v4, 32 bitop3:0x36
	v_bitop3_b32 v127, v184, v4, 64 bitop3:0x36
	v_cmp_gt_u32_e64 s[6:7], 32, v5
	v_lshl_add_u32 v123, v6, 2, v122
	v_add3_u32 v129, v2, s0, v0
	v_mov_b32_e32 v0, v185
	v_mov_b32_e32 v1, v185
	v_mov_b32_e32 v2, v185
	v_mov_b32_e32 v3, v185
	v_mov_b32_e32 v4, v185
	v_mov_b32_e32 v5, v185
	v_mov_b32_e32 v6, v185
	v_mov_b32_e32 v7, v185
	v_mov_b32_e32 v8, v185
	v_mov_b32_e32 v9, v185
	v_mov_b32_e32 v10, v185
	v_mov_b32_e32 v11, v185
	v_mov_b32_e32 v12, v185
	v_mov_b32_e32 v13, v185
	v_mov_b64_e32 v[30:31], v[14:15]
	v_mov_b64_e32 v[46:47], v[14:15]
	v_mov_b64_e32 v[62:63], v[14:15]
	v_mov_b64_e32 v[28:29], v[12:13]
	v_mov_b64_e32 v[26:27], v[10:11]
	v_mov_b64_e32 v[24:25], v[8:9]
	v_mov_b64_e32 v[22:23], v[6:7]
	v_mov_b64_e32 v[20:21], v[4:5]
	v_mov_b64_e32 v[18:19], v[2:3]
	v_mov_b64_e32 v[16:17], v[0:1]
	v_mov_b64_e32 v[44:45], v[12:13]
	v_mov_b64_e32 v[42:43], v[10:11]
	v_mov_b64_e32 v[40:41], v[8:9]
	v_mov_b64_e32 v[38:39], v[6:7]
	v_mov_b64_e32 v[36:37], v[4:5]
	v_mov_b64_e32 v[34:35], v[2:3]
	v_mov_b64_e32 v[32:33], v[0:1]
	v_mov_b64_e32 v[60:61], v[12:13]
	v_mov_b64_e32 v[58:59], v[10:11]
	v_mov_b64_e32 v[56:57], v[8:9]
	v_mov_b64_e32 v[54:55], v[6:7]
	v_mov_b64_e32 v[52:53], v[4:5]
	v_mov_b64_e32 v[50:51], v[2:3]
	v_mov_b64_e32 v[48:49], v[0:1]
	v_mov_b32_e32 v160, 0x80000000
	v_mov_b32_e32 v161, 0x80000000
	v_mov_b32_e32 v162, 0x80000000
	v_mov_b32_e32 v163, 0x80000000
	v_mov_b32_e32 v164, 0x80000000
	v_mov_b32_e32 v165, 0x80000000
	v_mov_b32_e32 v166, 0x80000000
	v_mov_b32_e32 v167, 0x80000000
	v_mov_b32_e32 v168, 0x80000000
	v_mov_b32_e32 v169, 0x80000000
	v_mov_b32_e32 v170, 0x80000000
	v_mov_b32_e32 v171, 0x80000000
	v_mov_b32_e32 v172, 0x80000000
	v_mov_b32_e32 v173, 0x80000000
	v_mov_b32_e32 v174, 0x80000000
	v_mov_b32_e32 v175, 0x80000000
	v_readlane_b32 s54, v254, 48
	s_waitcnt vmcnt(0) lgkmcnt(0)
	s_barrier
	s_and_b32 s53, s5, 1
	v_add_u32_e32 v120, v124, v125
	ds_read_b128 v[132:135], v120 offset:0
	ds_read_b128 v[136:139], v120 offset:0x1000
	s_cmp_eq_u32 s5, 31
	s_movk_i32 s0, 0x2000
	s_cbranch_scc1 .LBB0_152

.LBB0_152:
	v_add_u32_e32 v80, s0, v124
	v_add_u32_e32 v82, v80, v126
	ds_read_b128 v[140:143], v82 offset:0
	ds_read_b128 v[146:149], v82 offset:0x1000
	s_waitcnt lgkmcnt(2)
	v_add_u32_e32 v120, v80, v127
	v_add_u32_e32 v150, v80, v128
	v_mfma_f32_32x32x16_bf16 v[80:95], v[132:135], v[96:99], v[160:175]
	ds_read_b128 v[132:135], v120 offset:0
	v_mfma_f32_32x32x16_bf16 v[64:79], v[136:139], v[96:99], v[160:175]
	ds_read_b128 v[136:139], v120 offset:0x1000
	s_waitcnt lgkmcnt(2)
	v_mfma_f32_32x32x16_bf16 v[80:95], v[140:143], v[100:103], v[80:95]
	ds_read_b128 v[140:143], v150 offset:0
	v_mfma_f32_32x32x16_bf16 v[64:79], v[146:149], v[100:103], v[64:79]
	ds_read_b128 v[146:149], v150 offset:0x1000
	s_waitcnt lgkmcnt(2)
	v_mfma_f32_32x32x16_bf16 v[80:95], v[132:135], v[104:107], v[80:95]
	s_waitcnt lgkmcnt(0)
	v_mfma_f32_32x32x16_bf16 v[64:79], v[136:139], v[104:107], v[64:79]
	v_mfma_f32_32x32x16_bf16 v[80:95], v[140:143], v[108:111], v[80:95]
	s_cmp_eq_u32 s5, 0
	s_cselect_b64 s[24:25], -1, 0
	s_cmp_lg_u32 s5, 0
	v_mfma_f32_32x32x16_bf16 v[64:79], v[146:149], v[108:111], v[64:79]
	s_nop 7
	v_max_f32_e32 v120, v80, v81
	v_max3_f32 v120, v120, v82, v83
	v_max3_f32 v120, v120, v84, v85
	v_max3_f32 v120, v120, v86, v87
	v_max3_f32 v120, v120, v88, v89
	v_max3_f32 v120, v120, v90, v91
	v_max3_f32 v120, v120, v92, v93
	v_max3_f32 v120, v120, v94, v95
	v_max3_f32 v120, v120, v64, v65
	v_max3_f32 v120, v120, v66, v67
	v_max3_f32 v120, v120, v68, v69
	v_max3_f32 v120, v120, v70, v71
	v_max3_f32 v120, v120, v72, v73
	v_max3_f32 v120, v120, v74, v75
	v_max3_f32 v120, v120, v76, v77
	v_max3_f32 v120, v120, v78, v79
	v_mov_b32_e32 v132, v120
	s_nop 1
	v_permlane32_swap_b32_e32 v120, v132
	v_max_f32_e32 v132, v120, v132
	s_cbranch_scc0 .LBB0_157
	v_cmp_ge_f32_e32 vcc, s62, v132
	s_cmp_lg_u64 vcc, exec
	s_mov_b64 s[34:35], 0
	s_mov_b64 s[30:31], 0
	s_cbranch_scc1 .LBB0_158
	v_mov_b32_e32 v132, 1.0
	s_branch .LBB0_164

.LBB0_164:
	v_exp_f32_e32 v80, v80
	v_exp_f32_e32 v81, v81
	v_exp_f32_e32 v82, v82
	v_exp_f32_e32 v83, v83
	v_exp_f32_e32 v84, v84
	v_exp_f32_e32 v120, v64
	v_add_f32_e32 v64, 0, v80
	v_exp_f32_e32 v85, v85
	v_add_f32_e32 v64, v81, v64
	v_exp_f32_e32 v86, v86
	v_add_f32_e32 v64, v82, v64
	v_exp_f32_e32 v87, v87
	v_add_f32_e32 v64, v83, v64
	v_exp_f32_e32 v88, v88
	v_add_f32_e32 v64, v84, v64
	v_exp_f32_e32 v89, v89
	v_add_f32_e32 v64, v85, v64
	v_exp_f32_e32 v90, v90
	v_add_f32_e32 v64, v86, v64
	v_exp_f32_e32 v91, v91
	v_add_f32_e32 v64, v87, v64
	v_exp_f32_e32 v92, v92
	v_add_f32_e32 v64, v88, v64
	v_exp_f32_e32 v93, v93
	v_add_f32_e32 v64, v89, v64
	v_exp_f32_e32 v94, v94
	v_add_f32_e32 v64, v90, v64
	v_exp_f32_e32 v95, v95
	v_add_f32_e32 v64, v91, v64
	v_add_f32_e32 v64, v92, v64
	v_exp_f32_e32 v65, v65
	v_add_f32_e32 v64, v93, v64
	v_exp_f32_e32 v133, v66
	v_add_f32_e32 v64, v94, v64
	v_exp_f32_e32 v134, v67
	v_add_f32_e32 v64, v95, v64
	v_exp_f32_e32 v135, v68
	v_add_f32_e32 v64, v120, v64
	v_exp_f32_e32 v136, v69
	v_add_f32_e32 v64, v65, v64
	v_exp_f32_e32 v137, v70
	v_add_f32_e32 v64, v133, v64
	v_exp_f32_e32 v138, v71
	v_add_f32_e32 v64, v134, v64
	v_exp_f32_e32 v139, v72
	v_add_f32_e32 v64, v135, v64
	v_exp_f32_e32 v140, v73
	v_add_f32_e32 v64, v136, v64
	v_exp_f32_e32 v141, v74
	v_add_f32_e32 v64, v137, v64
	v_exp_f32_e32 v142, v75
	v_add_f32_e32 v64, v138, v64
	v_exp_f32_e32 v143, v76
	v_add_f32_e32 v64, v139, v64
	v_exp_f32_e32 v146, v77
	v_add_f32_e32 v64, v140, v64
	v_exp_f32_e32 v147, v78
	v_add_f32_e32 v64, v141, v64
	v_exp_f32_e32 v148, v79
	v_add_f32_e32 v64, v142, v64
	v_add_f32_e32 v64, v143, v64
	v_add_f32_e32 v64, v146, v64
	v_add_f32_e32 v64, v147, v64
	v_add_f32_e32 v64, v148, v64
	v_mov_b32_e32 v66, v64
	s_nop 1
	v_permlane32_swap_b32_e32 v64, v66
	v_add_f32_e32 v64, v64, v66
	s_add_i32 s5, s5, 1
	v_fmac_f32_e32 v64, v131, v132
	v_cvt_pk_bf16_f32 v66, v80, v81
	v_cvt_pk_bf16_f32 v67, v82, v83
	v_cvt_pk_bf16_f32 v68, v84, v85
	v_cvt_pk_bf16_f32 v69, v86, v87
	v_cvt_pk_bf16_f32 v70, v88, v89
	v_cvt_pk_bf16_f32 v71, v90, v91
	v_cvt_pk_bf16_f32 v72, v92, v93
	v_cvt_pk_bf16_f32 v73, v94, v95
	v_cvt_pk_bf16_f32 v74, v120, v65
	v_cvt_pk_bf16_f32 v75, v133, v134
	v_cvt_pk_bf16_f32 v76, v135, v136
	v_cvt_pk_bf16_f32 v77, v137, v138
	v_cvt_pk_bf16_f32 v78, v139, v140
	v_cvt_pk_bf16_f32 v79, v141, v142
	v_cvt_pk_bf16_f32 v80, v143, v146
	v_cvt_pk_bf16_f32 v81, v147, v148
	s_nop 0
	v_permlane32_swap_b32_e32 v66, v68
	v_permlane32_swap_b32_e32 v67, v69
	v_permlane32_swap_b32_e32 v70, v72
	v_permlane32_swap_b32_e32 v71, v73
	v_permlane32_swap_b32_e32 v74, v76
	v_permlane32_swap_b32_e32 v75, v77
	v_permlane32_swap_b32_e32 v78, v80
	v_permlane32_swap_b32_e32 v79, v81
	v_lshl_add_u32 v65, s53, 14, v129
	ds_read_b64_tr_b16 v[82:83], v65 offset:0
	ds_read_b64_tr_b16 v[84:85], v65 offset:0x800
	ds_read_b64_tr_b16 v[86:87], v65 offset:0x1000
	ds_read_b64_tr_b16 v[88:89], v65 offset:0x1800
	ds_read_b64_tr_b16 v[90:91], v65 offset:0x2000
	ds_read_b64_tr_b16 v[92:93], v65 offset:0x2800
	ds_read_b64_tr_b16 v[132:133], v65 offset:0x3000
	ds_read_b64_tr_b16 v[134:135], v65 offset:0x3800
	ds_read_b64_tr_b16 v[136:137], v65 offset:0x200
	ds_read_b64_tr_b16 v[138:139], v65 offset:0xa00
	ds_read_b64_tr_b16 v[140:141], v65 offset:0x1200
	ds_read_b64_tr_b16 v[142:143], v65 offset:0x1a00
	ds_read_b64_tr_b16 v[146:147], v65 offset:0x2200
	ds_read_b64_tr_b16 v[148:149], v65 offset:0x2a00
	ds_read_b64_tr_b16 v[150:151], v65 offset:0x3200
	ds_read_b64_tr_b16 v[152:153], v65 offset:0x3a00
	s_waitcnt lgkmcnt(8)
	s_nop 0
	v_mfma_f32_32x32x16_bf16 v[48:63], v[66:69], v[82:85], v[48:63]
	ds_read_b64_tr_b16 v[82:83], v65 offset:0x400
	ds_read_b64_tr_b16 v[84:85], v65 offset:0xc00
	v_mfma_f32_32x32x16_bf16 v[48:63], v[70:73], v[86:89], v[48:63]
	ds_read_b64_tr_b16 v[86:87], v65 offset:0x1400
	ds_read_b64_tr_b16 v[88:89], v65 offset:0x1c00
	v_mfma_f32_32x32x16_bf16 v[48:63], v[74:77], v[90:93], v[48:63]
	ds_read_b64_tr_b16 v[90:91], v65 offset:0x2400
	ds_read_b64_tr_b16 v[92:93], v65 offset:0x2c00
	v_mfma_f32_32x32x16_bf16 v[48:63], v[78:81], v[132:135], v[48:63]
	ds_read_b64_tr_b16 v[132:133], v65 offset:0x3400
	ds_read_b64_tr_b16 v[134:135], v65 offset:0x3c00
	s_waitcnt lgkmcnt(8)
	v_mfma_f32_32x32x16_bf16 v[32:47], v[66:69], v[136:139], v[32:47]
	ds_read_b64_tr_b16 v[136:137], v65 offset:0x600
	ds_read_b64_tr_b16 v[138:139], v65 offset:0xe00
	v_mfma_f32_32x32x16_bf16 v[32:47], v[70:73], v[140:143], v[32:47]
	ds_read_b64_tr_b16 v[140:141], v65 offset:0x1600
	ds_read_b64_tr_b16 v[142:143], v65 offset:0x1e00
	v_mfma_f32_32x32x16_bf16 v[32:47], v[74:77], v[146:149], v[32:47]
	ds_read_b64_tr_b16 v[146:147], v65 offset:0x2600
	ds_read_b64_tr_b16 v[148:149], v65 offset:0x2e00
	v_mfma_f32_32x32x16_bf16 v[32:47], v[78:81], v[150:153], v[32:47]
	ds_read_b64_tr_b16 v[150:151], v65 offset:0x3600
	ds_read_b64_tr_b16 v[152:153], v65 offset:0x3e00
	s_waitcnt lgkmcnt(8)
	v_mfma_f32_32x32x16_bf16 v[16:31], v[66:69], v[82:85], v[16:31]
	s_waitcnt lgkmcnt(0)
	v_mfma_f32_32x32x16_bf16 v[16:31], v[70:73], v[86:89], v[16:31]
	v_mfma_f32_32x32x16_bf16 v[16:31], v[74:77], v[90:93], v[16:31]
	v_mfma_f32_32x32x16_bf16 v[16:31], v[78:81], v[132:135], v[16:31]
	v_mfma_f32_32x32x16_bf16 v[0:15], v[66:69], v[136:139], v[0:15]
	s_waitcnt vmcnt(0)
	s_add_i32 s67, s67, 0x8000
	s_cmp_eq_u32 s5, 32
	s_waitcnt vmcnt(0) lgkmcnt(0)
	s_barrier
	s_and_b32 s1, s5, 1
	s_lshl_b32 s1, s1, 13
	v_add3_u32 v120, v124, v125, s1
	ds_read_b128 v[132:135], v120 offset:0
	ds_read_b128 v[136:139], v120 offset:0x1000
	s_cmp_eq_u32 s5, 32
	v_mfma_f32_32x32x16_bf16 v[0:15], v[70:73], v[140:143], v[0:15]
	v_mfma_f32_32x32x16_bf16 v[0:15], v[74:77], v[146:149], v[0:15]
	v_mfma_f32_32x32x16_bf16 v[0:15], v[78:81], v[150:153], v[0:15]
	s_cbranch_scc1 .LBB0_166
	v_mov_b32_e32 v131, v64
	s_and_b32 s53, s5, 1
	s_cmp_eq_u32 s5, 31
	s_movk_i32 s0, 0x2000
	s_cbranch_scc0 .LBB0_151
	s_branch .LBB0_152
.LBB0_166:
	s_and_saveexec_b64 s[0:1], s[6:7]
	v_readlane_b32 s53, v254, 49
	ds_write_b32 v123, v64
	s_or_b64 exec, exec, s[0:1]
	s_waitcnt lgkmcnt(0)
	global_load_dwordx4 v[68:71], v[112:113], off
	global_load_dwordx4 v[72:75], v[112:113], off offset:16
	global_load_dwordx4 v[76:79], v[112:113], off offset:32
	global_load_dwordx4 v[80:83], v[112:113], off offset:48
	global_load_dwordx4 v[84:87], v[112:113], off offset:64
	global_load_dwordx4 v[88:91], v[112:113], off offset:80
	global_load_dwordx4 v[92:95], v[112:113], off offset:96
	global_load_dwordx4 v[96:99], v[112:113], off offset:112
	global_load_dwordx4 v[100:103], v[112:113], off offset:128
	global_load_dwordx4 v[104:107], v[112:113], off offset:144
	global_load_dwordx4 v[108:111], v[112:113], off offset:160
	global_load_dwordx4 v[130:133], v[112:113], off offset:176
	global_load_dwordx4 v[134:137], v[112:113], off offset:192
	global_load_dwordx4 v[138:141], v[112:113], off offset:208
	global_load_dwordx4 v[146:149], v[112:113], off offset:224
	global_load_dwordx4 v[150:153], v[112:113], off offset:240
	v_and_b32_e32 v66, 31, v121
	v_lshlrev_b32_e32 v67, 2, v66
	global_load_dword v154, v67, s[10:11]
	global_load_dword v156, v67, s[10:11] offset:128
	global_load_dword v158, v67, s[10:11] offset:256
	global_load_dword v178, v67, s[10:11] offset:384
	v_add_u32_e32 v65, v122, v184
	s_waitcnt lgkmcnt(0)
	ds_read_b128 v[160:163], v65
	ds_read_b128 v[164:167], v65 offset:32
	ds_read_b128 v[168:171], v65 offset:64
	ds_read_b128 v[172:175], v65 offset:96
	v_ashrrev_i32_e32 v176, 1, v121
	v_and_b32_e32 v176, 0xffffffe0, v176
	v_ashrrev_i32_e32 v177, 31, v176
	v_lshl_add_u64 v[176:177], s[22:23], 0, v[176:177]
	v_lshrrev_b32_e32 v180, 3, v121
	v_and_or_b32 v176, v180, 4, v176
	v_lshlrev_b64 v[176:177], 11, v[176:177]
	v_lshl_add_u64 v[176:177], s[8:9], 0, v[176:177]
	s_lshl_b32 s88, s65, 1
	v_lshl_add_u64 v[176:177], v[176:177], 0, s[88:89]
	v_lshlrev_b32_e32 v184, 1, v66
	v_lshl_add_u64 v[176:177], v[176:177], 0, v[184:185]
	s_waitcnt lgkmcnt(0)
	v_rcp_f32_e32 v160, v160
	v_rcp_f32_e32 v161, v161
	v_rcp_f32_e32 v162, v162
	v_rcp_f32_e32 v163, v163
	v_rcp_f32_e32 v164, v164
	v_rcp_f32_e32 v165, v165
	v_rcp_f32_e32 v166, v166
	v_rcp_f32_e32 v167, v167
	v_rcp_f32_e32 v168, v168
	v_rcp_f32_e32 v169, v169
	v_rcp_f32_e32 v170, v170
	v_rcp_f32_e32 v171, v171
	v_rcp_f32_e32 v172, v172
	v_rcp_f32_e32 v173, v173
	v_rcp_f32_e32 v174, v174
	v_rcp_f32_e32 v175, v175
	v_pk_mul_f32 v[48:49], v[48:49], v[160:161]
	v_pk_mul_f32 v[50:51], v[50:51], v[162:163]
	v_pk_mul_f32 v[52:53], v[52:53], v[164:165]
	v_pk_mul_f32 v[54:55], v[54:55], v[166:167]
	v_pk_mul_f32 v[56:57], v[56:57], v[168:169]
	v_pk_mul_f32 v[58:59], v[58:59], v[170:171]
	v_pk_mul_f32 v[60:61], v[60:61], v[172:173]
	v_pk_mul_f32 v[62:63], v[62:63], v[174:175]
	v_pk_mul_f32 v[32:33], v[32:33], v[160:161]
	v_pk_mul_f32 v[34:35], v[34:35], v[162:163]
	v_pk_mul_f32 v[36:37], v[36:37], v[164:165]
	v_pk_mul_f32 v[38:39], v[38:39], v[166:167]
	v_pk_mul_f32 v[40:41], v[40:41], v[168:169]
	v_pk_mul_f32 v[42:43], v[42:43], v[170:171]
	v_pk_mul_f32 v[44:45], v[44:45], v[172:173]
	v_pk_mul_f32 v[46:47], v[46:47], v[174:175]
	v_pk_mul_f32 v[16:17], v[16:17], v[160:161]
	v_pk_mul_f32 v[18:19], v[18:19], v[162:163]
	v_pk_mul_f32 v[20:21], v[20:21], v[164:165]
	v_pk_mul_f32 v[22:23], v[22:23], v[166:167]
	v_pk_mul_f32 v[24:25], v[24:25], v[168:169]
	v_pk_mul_f32 v[26:27], v[26:27], v[170:171]
	v_pk_mul_f32 v[28:29], v[28:29], v[172:173]
	v_pk_mul_f32 v[30:31], v[30:31], v[174:175]
	v_pk_mul_f32 v[0:1], v[0:1], v[160:161]
	v_pk_mul_f32 v[2:3], v[2:3], v[162:163]
	v_pk_mul_f32 v[4:5], v[4:5], v[164:165]
	v_pk_mul_f32 v[6:7], v[6:7], v[166:167]
	v_pk_mul_f32 v[8:9], v[8:9], v[168:169]
	v_pk_mul_f32 v[10:11], v[10:11], v[170:171]
	v_pk_mul_f32 v[12:13], v[12:13], v[172:173]
	v_pk_mul_f32 v[14:15], v[14:15], v[174:175]
	s_waitcnt vmcnt(0)
	v_mul_f32_e32 v154, v157, v154
	v_mul_f32_e32 v156, v157, v156
	v_mul_f32_e32 v158, v157, v158
	v_mul_f32_e32 v178, v157, v178
	v_pk_fma_f32 v[48:49], v[144:145], v[48:49], v[68:69] neg_lo:[1,0,0] neg_hi:[1,0,0]
	v_pk_fma_f32 v[50:51], v[144:145], v[50:51], v[70:71] neg_lo:[1,0,0] neg_hi:[1,0,0]
	v_pk_fma_f32 v[52:53], v[144:145], v[52:53], v[72:73] neg_lo:[1,0,0] neg_hi:[1,0,0]
	v_pk_fma_f32 v[54:55], v[144:145], v[54:55], v[74:75] neg_lo:[1,0,0] neg_hi:[1,0,0]
	v_pk_fma_f32 v[56:57], v[144:145], v[56:57], v[76:77] neg_lo:[1,0,0] neg_hi:[1,0,0]
	v_pk_fma_f32 v[58:59], v[144:145], v[58:59], v[78:79] neg_lo:[1,0,0] neg_hi:[1,0,0]
	v_pk_fma_f32 v[60:61], v[144:145], v[60:61], v[80:81] neg_lo:[1,0,0] neg_hi:[1,0,0]
	v_pk_fma_f32 v[62:63], v[144:145], v[62:63], v[82:83] neg_lo:[1,0,0] neg_hi:[1,0,0]
	v_pk_fma_f32 v[32:33], v[144:145], v[32:33], v[84:85] neg_lo:[1,0,0] neg_hi:[1,0,0]
	v_pk_fma_f32 v[34:35], v[144:145], v[34:35], v[86:87] neg_lo:[1,0,0] neg_hi:[1,0,0]
	v_pk_fma_f32 v[36:37], v[144:145], v[36:37], v[88:89] neg_lo:[1,0,0] neg_hi:[1,0,0]
	v_pk_fma_f32 v[38:39], v[144:145], v[38:39], v[90:91] neg_lo:[1,0,0] neg_hi:[1,0,0]
	v_pk_fma_f32 v[40:41], v[144:145], v[40:41], v[92:93] neg_lo:[1,0,0] neg_hi:[1,0,0]
	v_pk_fma_f32 v[42:43], v[144:145], v[42:43], v[94:95] neg_lo:[1,0,0] neg_hi:[1,0,0]
	v_pk_fma_f32 v[44:45], v[144:145], v[44:45], v[96:97] neg_lo:[1,0,0] neg_hi:[1,0,0]
	v_pk_fma_f32 v[46:47], v[144:145], v[46:47], v[98:99] neg_lo:[1,0,0] neg_hi:[1,0,0]
	v_pk_fma_f32 v[16:17], v[144:145], v[16:17], v[100:101] neg_lo:[1,0,0] neg_hi:[1,0,0]
	v_pk_fma_f32 v[18:19], v[144:145], v[18:19], v[102:103] neg_lo:[1,0,0] neg_hi:[1,0,0]
	v_pk_fma_f32 v[20:21], v[144:145], v[20:21], v[104:105] neg_lo:[1,0,0] neg_hi:[1,0,0]
	v_pk_fma_f32 v[22:23], v[144:145], v[22:23], v[106:107] neg_lo:[1,0,0] neg_hi:[1,0,0]
	v_pk_fma_f32 v[24:25], v[144:145], v[24:25], v[108:109] neg_lo:[1,0,0] neg_hi:[1,0,0]
	v_pk_fma_f32 v[26:27], v[144:145], v[26:27], v[110:111] neg_lo:[1,0,0] neg_hi:[1,0,0]
	v_pk_fma_f32 v[28:29], v[144:145], v[28:29], v[130:131] neg_lo:[1,0,0] neg_hi:[1,0,0]
	v_pk_fma_f32 v[30:31], v[144:145], v[30:31], v[132:133] neg_lo:[1,0,0] neg_hi:[1,0,0]
	v_pk_fma_f32 v[0:1], v[144:145], v[0:1], v[134:135] neg_lo:[1,0,0] neg_hi:[1,0,0]
	v_pk_fma_f32 v[2:3], v[144:145], v[2:3], v[136:137] neg_lo:[1,0,0] neg_hi:[1,0,0]
	v_pk_fma_f32 v[4:5], v[144:145], v[4:5], v[138:139] neg_lo:[1,0,0] neg_hi:[1,0,0]
	v_pk_fma_f32 v[6:7], v[144:145], v[6:7], v[140:141] neg_lo:[1,0,0] neg_hi:[1,0,0]
	v_pk_fma_f32 v[8:9], v[144:145], v[8:9], v[146:147] neg_lo:[1,0,0] neg_hi:[1,0,0]
	v_pk_fma_f32 v[10:11], v[144:145], v[10:11], v[148:149] neg_lo:[1,0,0] neg_hi:[1,0,0]
	v_pk_fma_f32 v[12:13], v[144:145], v[12:13], v[150:151] neg_lo:[1,0,0] neg_hi:[1,0,0]
	v_pk_fma_f32 v[14:15], v[144:145], v[14:15], v[152:153] neg_lo:[1,0,0] neg_hi:[1,0,0]
	v_pk_mul_f32 v[68:69], v[48:49], v[48:49]
	v_pk_mul_f32 v[70:71], v[50:51], v[50:51]
	v_pk_mul_f32 v[72:73], v[52:53], v[52:53]
	v_pk_mul_f32 v[74:75], v[54:55], v[54:55]
	v_pk_mul_f32 v[76:77], v[56:57], v[56:57]
	v_pk_mul_f32 v[78:79], v[58:59], v[58:59]
	v_pk_mul_f32 v[80:81], v[60:61], v[60:61]
	v_pk_mul_f32 v[82:83], v[62:63], v[62:63]
	v_pk_fma_f32 v[68:69], v[32:33], v[32:33], v[68:69]
	v_pk_fma_f32 v[70:71], v[34:35], v[34:35], v[70:71]
	v_pk_fma_f32 v[72:73], v[36:37], v[36:37], v[72:73]
	v_pk_fma_f32 v[74:75], v[38:39], v[38:39], v[74:75]
	v_pk_fma_f32 v[76:77], v[40:41], v[40:41], v[76:77]
	v_pk_fma_f32 v[78:79], v[42:43], v[42:43], v[78:79]
	v_pk_fma_f32 v[80:81], v[44:45], v[44:45], v[80:81]
	v_pk_fma_f32 v[82:83], v[46:47], v[46:47], v[82:83]
	v_pk_fma_f32 v[68:69], v[16:17], v[16:17], v[68:69]
	v_pk_fma_f32 v[70:71], v[18:19], v[18:19], v[70:71]
	v_pk_fma_f32 v[72:73], v[20:21], v[20:21], v[72:73]
	v_pk_fma_f32 v[74:75], v[22:23], v[22:23], v[74:75]
	v_pk_fma_f32 v[76:77], v[24:25], v[24:25], v[76:77]
	v_pk_fma_f32 v[78:79], v[26:27], v[26:27], v[78:79]
	v_pk_fma_f32 v[80:81], v[28:29], v[28:29], v[80:81]
	v_pk_fma_f32 v[82:83], v[30:31], v[30:31], v[82:83]
	v_pk_fma_f32 v[68:69], v[0:1], v[0:1], v[68:69]
	v_pk_fma_f32 v[70:71], v[2:3], v[2:3], v[70:71]
	v_pk_fma_f32 v[72:73], v[4:5], v[4:5], v[72:73]
	v_pk_fma_f32 v[74:75], v[6:7], v[6:7], v[74:75]
	v_pk_fma_f32 v[76:77], v[8:9], v[8:9], v[76:77]
	v_pk_fma_f32 v[78:79], v[10:11], v[10:11], v[78:79]
	v_pk_fma_f32 v[80:81], v[12:13], v[12:13], v[80:81]
	v_pk_fma_f32 v[82:83], v[14:15], v[14:15], v[82:83]
	v_add_f32_dpp v68, v68, v68 quad_perm:[1,0,3,2] row_mask:0xf bank_mask:0xf
	v_add_f32_dpp v69, v69, v69 quad_perm:[1,0,3,2] row_mask:0xf bank_mask:0xf
	v_add_f32_dpp v70, v70, v70 quad_perm:[1,0,3,2] row_mask:0xf bank_mask:0xf
	v_add_f32_dpp v71, v71, v71 quad_perm:[1,0,3,2] row_mask:0xf bank_mask:0xf
	v_add_f32_dpp v72, v72, v72 quad_perm:[1,0,3,2] row_mask:0xf bank_mask:0xf
	v_add_f32_dpp v73, v73, v73 quad_perm:[1,0,3,2] row_mask:0xf bank_mask:0xf
	v_add_f32_dpp v74, v74, v74 quad_perm:[1,0,3,2] row_mask:0xf bank_mask:0xf
	v_add_f32_dpp v75, v75, v75 quad_perm:[1,0,3,2] row_mask:0xf bank_mask:0xf
	v_add_f32_dpp v76, v76, v76 quad_perm:[1,0,3,2] row_mask:0xf bank_mask:0xf
	v_add_f32_dpp v77, v77, v77 quad_perm:[1,0,3,2] row_mask:0xf bank_mask:0xf
	v_add_f32_dpp v78, v78, v78 quad_perm:[1,0,3,2] row_mask:0xf bank_mask:0xf
	v_add_f32_dpp v79, v79, v79 quad_perm:[1,0,3,2] row_mask:0xf bank_mask:0xf
	v_add_f32_dpp v80, v80, v80 quad_perm:[1,0,3,2] row_mask:0xf bank_mask:0xf
	v_add_f32_dpp v81, v81, v81 quad_perm:[1,0,3,2] row_mask:0xf bank_mask:0xf
	v_add_f32_dpp v82, v82, v82 quad_perm:[1,0,3,2] row_mask:0xf bank_mask:0xf
	v_add_f32_dpp v83, v83, v83 quad_perm:[1,0,3,2] row_mask:0xf bank_mask:0xf
	v_add_f32_dpp v68, v68, v68 quad_perm:[2,3,0,1] row_mask:0xf bank_mask:0xf
	v_add_f32_dpp v69, v69, v69 quad_perm:[2,3,0,1] row_mask:0xf bank_mask:0xf
	v_add_f32_dpp v70, v70, v70 quad_perm:[2,3,0,1] row_mask:0xf bank_mask:0xf
	v_add_f32_dpp v71, v71, v71 quad_perm:[2,3,0,1] row_mask:0xf bank_mask:0xf
	v_add_f32_dpp v72, v72, v72 quad_perm:[2,3,0,1] row_mask:0xf bank_mask:0xf
	v_add_f32_dpp v73, v73, v73 quad_perm:[2,3,0,1] row_mask:0xf bank_mask:0xf
	v_add_f32_dpp v74, v74, v74 quad_perm:[2,3,0,1] row_mask:0xf bank_mask:0xf
	v_add_f32_dpp v75, v75, v75 quad_perm:[2,3,0,1] row_mask:0xf bank_mask:0xf
	v_add_f32_dpp v76, v76, v76 quad_perm:[2,3,0,1] row_mask:0xf bank_mask:0xf
	v_add_f32_dpp v77, v77, v77 quad_perm:[2,3,0,1] row_mask:0xf bank_mask:0xf
	v_add_f32_dpp v78, v78, v78 quad_perm:[2,3,0,1] row_mask:0xf bank_mask:0xf
	v_add_f32_dpp v79, v79, v79 quad_perm:[2,3,0,1] row_mask:0xf bank_mask:0xf
	v_add_f32_dpp v80, v80, v80 quad_perm:[2,3,0,1] row_mask:0xf bank_mask:0xf
	v_add_f32_dpp v81, v81, v81 quad_perm:[2,3,0,1] row_mask:0xf bank_mask:0xf
	v_add_f32_dpp v82, v82, v82 quad_perm:[2,3,0,1] row_mask:0xf bank_mask:0xf
	v_add_f32_dpp v83, v83, v83 quad_perm:[2,3,0,1] row_mask:0xf bank_mask:0xf
	v_add_f32_dpp v68, v68, v68 row_half_mirror row_mask:0xf bank_mask:0xf
	v_add_f32_dpp v69, v69, v69 row_half_mirror row_mask:0xf bank_mask:0xf
	v_add_f32_dpp v70, v70, v70 row_half_mirror row_mask:0xf bank_mask:0xf
	v_add_f32_dpp v71, v71, v71 row_half_mirror row_mask:0xf bank_mask:0xf
	v_add_f32_dpp v72, v72, v72 row_half_mirror row_mask:0xf bank_mask:0xf
	v_add_f32_dpp v73, v73, v73 row_half_mirror row_mask:0xf bank_mask:0xf
	v_add_f32_dpp v74, v74, v74 row_half_mirror row_mask:0xf bank_mask:0xf
	v_add_f32_dpp v75, v75, v75 row_half_mirror row_mask:0xf bank_mask:0xf
	v_add_f32_dpp v76, v76, v76 row_half_mirror row_mask:0xf bank_mask:0xf
	v_add_f32_dpp v77, v77, v77 row_half_mirror row_mask:0xf bank_mask:0xf
	v_add_f32_dpp v78, v78, v78 row_half_mirror row_mask:0xf bank_mask:0xf
	v_add_f32_dpp v79, v79, v79 row_half_mirror row_mask:0xf bank_mask:0xf
	v_add_f32_dpp v80, v80, v80 row_half_mirror row_mask:0xf bank_mask:0xf
	v_add_f32_dpp v81, v81, v81 row_half_mirror row_mask:0xf bank_mask:0xf
	v_add_f32_dpp v82, v82, v82 row_half_mirror row_mask:0xf bank_mask:0xf
	v_add_f32_dpp v83, v83, v83 row_half_mirror row_mask:0xf bank_mask:0xf
	v_add_f32_dpp v68, v68, v68 row_mirror row_mask:0xf bank_mask:0xf
	v_add_f32_dpp v69, v69, v69 row_mirror row_mask:0xf bank_mask:0xf
	v_add_f32_dpp v70, v70, v70 row_mirror row_mask:0xf bank_mask:0xf
	v_add_f32_dpp v71, v71, v71 row_mirror row_mask:0xf bank_mask:0xf
	v_add_f32_dpp v72, v72, v72 row_mirror row_mask:0xf bank_mask:0xf
	v_add_f32_dpp v73, v73, v73 row_mirror row_mask:0xf bank_mask:0xf
	v_add_f32_dpp v74, v74, v74 row_mirror row_mask:0xf bank_mask:0xf
	v_add_f32_dpp v75, v75, v75 row_mirror row_mask:0xf bank_mask:0xf
	v_add_f32_dpp v76, v76, v76 row_mirror row_mask:0xf bank_mask:0xf
	v_add_f32_dpp v77, v77, v77 row_mirror row_mask:0xf bank_mask:0xf
	v_add_f32_dpp v78, v78, v78 row_mirror row_mask:0xf bank_mask:0xf
	v_add_f32_dpp v79, v79, v79 row_mirror row_mask:0xf bank_mask:0xf
	v_add_f32_dpp v80, v80, v80 row_mirror row_mask:0xf bank_mask:0xf
	v_add_f32_dpp v81, v81, v81 row_mirror row_mask:0xf bank_mask:0xf
	v_add_f32_dpp v82, v82, v82 row_mirror row_mask:0xf bank_mask:0xf
	v_add_f32_dpp v83, v83, v83 row_mirror row_mask:0xf bank_mask:0xf
	ds_swizzle_b32 v84, v68 offset:0x401f
	ds_swizzle_b32 v85, v69 offset:0x401f
	ds_swizzle_b32 v86, v70 offset:0x401f
	ds_swizzle_b32 v87, v71 offset:0x401f
	ds_swizzle_b32 v88, v72 offset:0x401f
	ds_swizzle_b32 v89, v73 offset:0x401f
	ds_swizzle_b32 v90, v74 offset:0x401f
	ds_swizzle_b32 v91, v75 offset:0x401f
	ds_swizzle_b32 v92, v76 offset:0x401f
	ds_swizzle_b32 v93, v77 offset:0x401f
	ds_swizzle_b32 v94, v78 offset:0x401f
	ds_swizzle_b32 v95, v79 offset:0x401f
	ds_swizzle_b32 v96, v80 offset:0x401f
	ds_swizzle_b32 v97, v81 offset:0x401f
	ds_swizzle_b32 v98, v82 offset:0x401f
	ds_swizzle_b32 v99, v83 offset:0x401f
	s_waitcnt lgkmcnt(0)
	v_pk_add_f32 v[68:69], v[68:69], v[84:85]
	v_pk_add_f32 v[70:71], v[70:71], v[86:87]
	v_pk_add_f32 v[72:73], v[72:73], v[88:89]
	v_pk_add_f32 v[74:75], v[74:75], v[90:91]
	v_pk_add_f32 v[76:77], v[76:77], v[92:93]
	v_pk_add_f32 v[78:79], v[78:79], v[94:95]
	v_pk_add_f32 v[80:81], v[80:81], v[96:97]
	v_pk_add_f32 v[82:83], v[82:83], v[98:99]
	v_fmamk_f32 v68, v68, 0x3c000000, v219
	v_fmamk_f32 v69, v69, 0x3c000000, v219
	v_fmamk_f32 v70, v70, 0x3c000000, v219
	v_fmamk_f32 v71, v71, 0x3c000000, v219
	v_fmamk_f32 v72, v72, 0x3c000000, v219
	v_fmamk_f32 v73, v73, 0x3c000000, v219
	v_fmamk_f32 v74, v74, 0x3c000000, v219
	v_fmamk_f32 v75, v75, 0x3c000000, v219
	v_fmamk_f32 v76, v76, 0x3c000000, v219
	v_fmamk_f32 v77, v77, 0x3c000000, v219
	v_fmamk_f32 v78, v78, 0x3c000000, v219
	v_fmamk_f32 v79, v79, 0x3c000000, v219
	v_fmamk_f32 v80, v80, 0x3c000000, v219
	v_fmamk_f32 v81, v81, 0x3c000000, v219
	v_fmamk_f32 v82, v82, 0x3c000000, v219
	v_fmamk_f32 v83, v83, 0x3c000000, v219
	v_rsq_f32_e32 v68, v68
	v_rsq_f32_e32 v69, v69
	v_rsq_f32_e32 v70, v70
	v_rsq_f32_e32 v71, v71
	v_rsq_f32_e32 v72, v72
	v_rsq_f32_e32 v73, v73
	v_rsq_f32_e32 v74, v74
	v_rsq_f32_e32 v75, v75
	v_rsq_f32_e32 v76, v76
	v_rsq_f32_e32 v77, v77
	v_rsq_f32_e32 v78, v78
	v_rsq_f32_e32 v79, v79
	v_rsq_f32_e32 v80, v80
	v_rsq_f32_e32 v81, v81
	v_rsq_f32_e32 v82, v82
	v_rsq_f32_e32 v83, v83
	v_pk_mul_f32 v[48:49], v[48:49], v[68:69]
	v_pk_mul_f32 v[50:51], v[50:51], v[70:71]
	v_pk_mul_f32 v[52:53], v[52:53], v[72:73]
	v_pk_mul_f32 v[54:55], v[54:55], v[74:75]
	v_pk_mul_f32 v[56:57], v[56:57], v[76:77]
	v_pk_mul_f32 v[58:59], v[58:59], v[78:79]
	v_pk_mul_f32 v[60:61], v[60:61], v[80:81]
	v_pk_mul_f32 v[62:63], v[62:63], v[82:83]
	v_pk_mul_f32 v[32:33], v[32:33], v[68:69]
	v_pk_mul_f32 v[34:35], v[34:35], v[70:71]
	v_pk_mul_f32 v[36:37], v[36:37], v[72:73]
	v_pk_mul_f32 v[38:39], v[38:39], v[74:75]
	v_pk_mul_f32 v[40:41], v[40:41], v[76:77]
	v_pk_mul_f32 v[42:43], v[42:43], v[78:79]
	v_pk_mul_f32 v[44:45], v[44:45], v[80:81]
	v_pk_mul_f32 v[46:47], v[46:47], v[82:83]
	v_pk_mul_f32 v[16:17], v[16:17], v[68:69]
	v_pk_mul_f32 v[18:19], v[18:19], v[70:71]
	v_pk_mul_f32 v[20:21], v[20:21], v[72:73]
	v_pk_mul_f32 v[22:23], v[22:23], v[74:75]
	v_pk_mul_f32 v[24:25], v[24:25], v[76:77]
	v_pk_mul_f32 v[26:27], v[26:27], v[78:79]
	v_pk_mul_f32 v[28:29], v[28:29], v[80:81]
	v_pk_mul_f32 v[30:31], v[30:31], v[82:83]
	v_pk_mul_f32 v[0:1], v[0:1], v[68:69]
	v_pk_mul_f32 v[2:3], v[2:3], v[70:71]
	v_pk_mul_f32 v[4:5], v[4:5], v[72:73]
	v_pk_mul_f32 v[6:7], v[6:7], v[74:75]
	v_pk_mul_f32 v[8:9], v[8:9], v[76:77]
	v_pk_mul_f32 v[10:11], v[10:11], v[78:79]
	v_pk_mul_f32 v[12:13], v[12:13], v[80:81]
	v_pk_mul_f32 v[14:15], v[14:15], v[82:83]
	v_pk_mul_f32 v[48:49], v[48:49], v[154:155] op_sel_hi:[1,0]
	v_pk_mul_f32 v[50:51], v[50:51], v[154:155] op_sel_hi:[1,0]
	v_pk_mul_f32 v[52:53], v[52:53], v[154:155] op_sel_hi:[1,0]
	v_pk_mul_f32 v[54:55], v[54:55], v[154:155] op_sel_hi:[1,0]
	v_pk_mul_f32 v[56:57], v[56:57], v[154:155] op_sel_hi:[1,0]
	v_pk_mul_f32 v[58:59], v[58:59], v[154:155] op_sel_hi:[1,0]
	v_pk_mul_f32 v[60:61], v[60:61], v[154:155] op_sel_hi:[1,0]
	v_pk_mul_f32 v[62:63], v[62:63], v[154:155] op_sel_hi:[1,0]
	v_pk_mul_f32 v[32:33], v[32:33], v[156:157] op_sel_hi:[1,0]
	v_pk_mul_f32 v[34:35], v[34:35], v[156:157] op_sel_hi:[1,0]
	v_pk_mul_f32 v[36:37], v[36:37], v[156:157] op_sel_hi:[1,0]
	v_pk_mul_f32 v[38:39], v[38:39], v[156:157] op_sel_hi:[1,0]
	v_pk_mul_f32 v[40:41], v[40:41], v[156:157] op_sel_hi:[1,0]
	v_pk_mul_f32 v[42:43], v[42:43], v[156:157] op_sel_hi:[1,0]
	v_pk_mul_f32 v[44:45], v[44:45], v[156:157] op_sel_hi:[1,0]
	v_pk_mul_f32 v[46:47], v[46:47], v[156:157] op_sel_hi:[1,0]
	v_pk_mul_f32 v[16:17], v[16:17], v[158:159] op_sel_hi:[1,0]
	v_pk_mul_f32 v[18:19], v[18:19], v[158:159] op_sel_hi:[1,0]
	v_pk_mul_f32 v[20:21], v[20:21], v[158:159] op_sel_hi:[1,0]
	v_pk_mul_f32 v[22:23], v[22:23], v[158:159] op_sel_hi:[1,0]
	v_pk_mul_f32 v[24:25], v[24:25], v[158:159] op_sel_hi:[1,0]
	v_pk_mul_f32 v[26:27], v[26:27], v[158:159] op_sel_hi:[1,0]
	v_pk_mul_f32 v[28:29], v[28:29], v[158:159] op_sel_hi:[1,0]
	v_pk_mul_f32 v[30:31], v[30:31], v[158:159] op_sel_hi:[1,0]
	v_pk_mul_f32 v[0:1], v[0:1], v[178:179] op_sel_hi:[1,0]
	v_pk_mul_f32 v[2:3], v[2:3], v[178:179] op_sel_hi:[1,0]
	v_pk_mul_f32 v[4:5], v[4:5], v[178:179] op_sel_hi:[1,0]
	v_pk_mul_f32 v[6:7], v[6:7], v[178:179] op_sel_hi:[1,0]
	v_pk_mul_f32 v[8:9], v[8:9], v[178:179] op_sel_hi:[1,0]
	v_pk_mul_f32 v[10:11], v[10:11], v[178:179] op_sel_hi:[1,0]
	v_pk_mul_f32 v[12:13], v[12:13], v[178:179] op_sel_hi:[1,0]
	v_pk_mul_f32 v[14:15], v[14:15], v[178:179] op_sel_hi:[1,0]
	v_cvt_pk_bf16_f32 v48, v48, v48
	v_cvt_pk_bf16_f32 v49, v49, v49
	v_cvt_pk_bf16_f32 v50, v50, v50
	v_cvt_pk_bf16_f32 v51, v51, v51
	v_cvt_pk_bf16_f32 v52, v52, v52
	v_cvt_pk_bf16_f32 v53, v53, v53
	v_cvt_pk_bf16_f32 v54, v54, v54
	v_cvt_pk_bf16_f32 v55, v55, v55
	v_cvt_pk_bf16_f32 v56, v56, v56
	v_cvt_pk_bf16_f32 v57, v57, v57
	v_cvt_pk_bf16_f32 v58, v58, v58
	v_cvt_pk_bf16_f32 v59, v59, v59
	v_cvt_pk_bf16_f32 v60, v60, v60
	v_cvt_pk_bf16_f32 v61, v61, v61
	v_cvt_pk_bf16_f32 v62, v62, v62
	v_cvt_pk_bf16_f32 v63, v63, v63
	v_cvt_pk_bf16_f32 v32, v32, v32
	v_cvt_pk_bf16_f32 v33, v33, v33
	v_cvt_pk_bf16_f32 v34, v34, v34
	v_cvt_pk_bf16_f32 v35, v35, v35
	v_cvt_pk_bf16_f32 v36, v36, v36
	v_cvt_pk_bf16_f32 v37, v37, v37
	v_cvt_pk_bf16_f32 v38, v38, v38
	v_cvt_pk_bf16_f32 v39, v39, v39
	v_cvt_pk_bf16_f32 v40, v40, v40
	v_cvt_pk_bf16_f32 v41, v41, v41
	v_cvt_pk_bf16_f32 v42, v42, v42
	v_cvt_pk_bf16_f32 v43, v43, v43
	v_cvt_pk_bf16_f32 v44, v44, v44
	v_cvt_pk_bf16_f32 v45, v45, v45
	v_cvt_pk_bf16_f32 v46, v46, v46
	v_cvt_pk_bf16_f32 v47, v47, v47
	v_cvt_pk_bf16_f32 v16, v16, v16
	v_cvt_pk_bf16_f32 v17, v17, v17
	v_cvt_pk_bf16_f32 v18, v18, v18
	v_cvt_pk_bf16_f32 v19, v19, v19
	v_cvt_pk_bf16_f32 v20, v20, v20
	v_cvt_pk_bf16_f32 v21, v21, v21
	v_cvt_pk_bf16_f32 v22, v22, v22
	v_cvt_pk_bf16_f32 v23, v23, v23
	v_cvt_pk_bf16_f32 v24, v24, v24
	v_cvt_pk_bf16_f32 v25, v25, v25
	v_cvt_pk_bf16_f32 v26, v26, v26
	v_cvt_pk_bf16_f32 v27, v27, v27
	v_cvt_pk_bf16_f32 v28, v28, v28
	v_cvt_pk_bf16_f32 v29, v29, v29
	v_cvt_pk_bf16_f32 v30, v30, v30
	v_cvt_pk_bf16_f32 v31, v31, v31
	v_cvt_pk_bf16_f32 v0, v0, v0
	v_cvt_pk_bf16_f32 v1, v1, v1
	v_cvt_pk_bf16_f32 v2, v2, v2
	v_cvt_pk_bf16_f32 v3, v3, v3
	v_cvt_pk_bf16_f32 v4, v4, v4
	v_cvt_pk_bf16_f32 v5, v5, v5
	v_cvt_pk_bf16_f32 v6, v6, v6
	v_cvt_pk_bf16_f32 v7, v7, v7
	v_cvt_pk_bf16_f32 v8, v8, v8
	v_cvt_pk_bf16_f32 v9, v9, v9
	v_cvt_pk_bf16_f32 v10, v10, v10
	v_cvt_pk_bf16_f32 v11, v11, v11
	v_cvt_pk_bf16_f32 v12, v12, v12
	v_cvt_pk_bf16_f32 v13, v13, v13
	v_cvt_pk_bf16_f32 v14, v14, v14
	v_cvt_pk_bf16_f32 v15, v15, v15
	global_store_short v[176:177], v48, off
	global_store_short v[176:177], v32, off offset:64
	global_store_short v[176:177], v16, off offset:128
	global_store_short v[176:177], v0, off offset:192
	global_store_short v[176:177], v49, off offset:2048
	global_store_short v[176:177], v33, off offset:2112
	global_store_short v[176:177], v17, off offset:2176
	global_store_short v[176:177], v1, off offset:2240
	s_mov_b64 s[0:1], 0x1000
	v_lshl_add_u64 v[182:183], v[176:177], 0, s[0:1]
	global_store_short v[182:183], v50, off
	global_store_short v[182:183], v34, off offset:64
	global_store_short v[182:183], v18, off offset:128
	global_store_short v[182:183], v2, off offset:192
	global_store_short v[182:183], v51, off offset:2048
	global_store_short v[182:183], v35, off offset:2112
	global_store_short v[182:183], v19, off offset:2176
	global_store_short v[182:183], v3, off offset:2240
	s_mov_b64 s[0:1], 0x4000
	v_lshl_add_u64 v[180:181], v[176:177], 0, s[0:1]
	global_store_short v[180:181], v52, off
	global_store_short v[180:181], v36, off offset:64
	global_store_short v[180:181], v20, off offset:128
	global_store_short v[180:181], v4, off offset:192
	global_store_short v[180:181], v53, off offset:2048
	global_store_short v[180:181], v37, off offset:2112
	global_store_short v[180:181], v21, off offset:2176
	global_store_short v[180:181], v5, off offset:2240
	s_mov_b64 s[0:1], 0x5000
	v_lshl_add_u64 v[182:183], v[176:177], 0, s[0:1]
	global_store_short v[182:183], v54, off
	global_store_short v[182:183], v38, off offset:64
	global_store_short v[182:183], v22, off offset:128
	global_store_short v[182:183], v6, off offset:192
	global_store_short v[182:183], v55, off offset:2048
	global_store_short v[182:183], v39, off offset:2112
	global_store_short v[182:183], v23, off offset:2176
	global_store_short v[182:183], v7, off offset:2240
	s_mov_b64 s[0:1], 0x8000
	v_lshl_add_u64 v[180:181], v[176:177], 0, s[0:1]
	global_store_short v[180:181], v56, off
	global_store_short v[180:181], v40, off offset:64
	global_store_short v[180:181], v24, off offset:128
	global_store_short v[180:181], v8, off offset:192
	global_store_short v[180:181], v57, off offset:2048
	global_store_short v[180:181], v41, off offset:2112
	global_store_short v[180:181], v25, off offset:2176
	global_store_short v[180:181], v9, off offset:2240
	s_mov_b64 s[0:1], 0x9000
	v_lshl_add_u64 v[182:183], v[176:177], 0, s[0:1]
	global_store_short v[182:183], v58, off
	global_store_short v[182:183], v42, off offset:64
	global_store_short v[182:183], v26, off offset:128
	global_store_short v[182:183], v10, off offset:192
	global_store_short v[182:183], v59, off offset:2048
	global_store_short v[182:183], v43, off offset:2112
	global_store_short v[182:183], v27, off offset:2176
	global_store_short v[182:183], v11, off offset:2240
	s_mov_b64 s[0:1], 0xc000
	v_lshl_add_u64 v[180:181], v[176:177], 0, s[0:1]
	global_store_short v[180:181], v60, off
	global_store_short v[180:181], v44, off offset:64
	global_store_short v[180:181], v28, off offset:128
	global_store_short v[180:181], v12, off offset:192
	global_store_short v[180:181], v61, off offset:2048
	global_store_short v[180:181], v45, off offset:2112
	global_store_short v[180:181], v29, off offset:2176
	global_store_short v[180:181], v13, off offset:2240
	s_mov_b64 s[0:1], 0xd000
	v_lshl_add_u64 v[182:183], v[176:177], 0, s[0:1]
	global_store_short v[182:183], v62, off
	global_store_short v[182:183], v46, off offset:64
	global_store_short v[182:183], v30, off offset:128
	global_store_short v[182:183], v14, off offset:192
	global_store_short v[182:183], v63, off offset:2048
	global_store_short v[182:183], v47, off offset:2112
	global_store_short v[182:183], v31, off offset:2176
	s_mov_b64 s[0:1], 0xd800
	v_mov_b32_e32 v2, v15
	v_lshl_add_u64 v[0:1], v[176:177], 0, s[0:1]
	s_branch .LBB0_129

.LBB0_192:
	v_lshlrev_b32_e32 v1, 2, v0
	s_add_i32 s4, s60, s2
	s_cmp_lt_i32 s4, 0x18000
	s_cselect_b32 s4, s4, s2
	v_readlane_b32 s0, v253, 49
	s_add_i32 s6, s0, s2
	s_cmp_lt_i32 s6, 0x18000
	s_cselect_b32 s6, s6, s2
	v_readlane_b32 s0, v254, 36
	s_add_i32 s8, s0, s2
	s_cmp_lt_i32 s8, 0x18000
	s_cselect_b32 s8, s8, s2
	s_lshl_b32 s12, s2, 3
	s_add_u32 s12, s26, s12
	s_addc_u32 s13, s27, 0
	global_load_dwordx2 v[2:3], v185, s[12:13]
	s_lshl_b32 s12, s4, 3
	s_add_u32 s12, s26, s12
	s_addc_u32 s13, s27, 0
	global_load_dwordx2 v[4:5], v185, s[12:13]
	s_lshl_b32 s12, s6, 3
	s_add_u32 s12, s26, s12
	s_addc_u32 s13, s27, 0
	global_load_dwordx2 v[6:7], v185, s[12:13]
	s_lshl_b32 s12, s8, 3
	s_add_u32 s12, s26, s12
	s_addc_u32 s13, s27, 0
	global_load_dwordx2 v[8:9], v185, s[12:13]
	s_mul_i32 s12, s2, 0x180
	s_add_u32 s14, s28, s12
	s_addc_u32 s15, s29, 0
	global_load_dword v10, v1, s[14:15]
	s_mul_i32 s12, s4, 0x180
	s_add_u32 s22, s28, s12
	s_addc_u32 s23, s29, 0
	global_load_dword v11, v1, s[22:23]
	s_mul_i32 s12, s6, 0x180
	s_add_u32 s24, s28, s12
	s_addc_u32 s25, s29, 0
	global_load_dword v12, v1, s[24:25]
	s_mul_i32 s12, s8, 0x180
	s_add_u32 s10, s28, s12
	s_addc_u32 s11, s29, 0
	global_load_dword v13, v1, s[10:11]
	s_waitcnt vmcnt(0)
	v_ffbh_u32_e32 v14, v3
	v_ffbh_u32_e32 v15, v5
	v_ffbh_u32_e32 v16, v7
	v_ffbh_u32_e32 v17, v9
	v_min_u32_e32 v14, 32, v14
	v_min_u32_e32 v15, 32, v15
	v_min_u32_e32 v16, 32, v16
	v_min_u32_e32 v17, 32, v17
	v_lshlrev_b64 v[2:3], v14, v[2:3]
	v_lshlrev_b64 v[4:5], v15, v[4:5]
	v_lshlrev_b64 v[6:7], v16, v[6:7]
	v_lshlrev_b64 v[8:9], v17, v[8:9]
	v_min_u32_e32 v2, 1, v2
	v_min_u32_e32 v4, 1, v4
	v_min_u32_e32 v6, 1, v6
	v_min_u32_e32 v8, 1, v8
	v_or_b32_e32 v2, v3, v2
	v_or_b32_e32 v4, v5, v4
	v_or_b32_e32 v6, v7, v6
	v_or_b32_e32 v8, v9, v8
	v_cvt_f32_u32_e32 v2, v2
	v_cvt_f32_u32_e32 v4, v4
	v_cvt_f32_u32_e32 v6, v6
	v_cvt_f32_u32_e32 v8, v8
	v_sub_u32_e32 v14, 32, v14
	v_sub_u32_e32 v15, 32, v15
	v_sub_u32_e32 v16, 32, v16
	v_sub_u32_e32 v17, 32, v17
	v_ldexp_f32 v14, v2, v14
	v_ldexp_f32 v15, v4, v15
	v_ldexp_f32 v16, v6, v16
	v_ldexp_f32 v17, v8, v17
	v_mul_f32_e32 v14, 0x33800000, v14
	v_mul_f32_e32 v15, 0x33800000, v15
	v_mul_f32_e32 v16, 0x33800000, v16
	v_mul_f32_e32 v17, 0x33800000, v17
	v_fmamk_f32 v14, v14, 0x3c000000, v219
	v_fmamk_f32 v15, v15, 0x3c000000, v219
	v_fmamk_f32 v16, v16, 0x3c000000, v219
	v_fmamk_f32 v17, v17, 0x3c000000, v219
	v_rsq_f32_e32 v14, v14
	v_rsq_f32_e32 v15, v15
	v_rsq_f32_e32 v16, v16
	v_rsq_f32_e32 v17, v17
	v_lshlrev_b32_e32 v2, 16, v10
	v_lshlrev_b32_e32 v4, 16, v11
	v_lshlrev_b32_e32 v6, 16, v12
	v_lshlrev_b32_e32 v8, 16, v13
	v_and_b32_e32 v10, 0xffff0000, v10
	v_and_b32_e32 v11, 0xffff0000, v11
	v_and_b32_e32 v12, 0xffff0000, v12
	v_and_b32_e32 v13, 0xffff0000, v13
	v_mul_f32_e32 v2, v14, v2
	v_mul_f32_e32 v4, v15, v4
	v_mul_f32_e32 v6, v16, v6
	v_mul_f32_e32 v8, v17, v8
	v_mul_f32_e32 v10, v14, v10
	v_mul_f32_e32 v11, v15, v11
	v_mul_f32_e32 v12, v16, v12
	v_mul_f32_e32 v13, v17, v13
	v_cvt_pk_bf16_f32 v10, v2, v10
	v_cvt_pk_bf16_f32 v11, v4, v11
	v_cvt_pk_bf16_f32 v12, v6, v12
	v_cvt_pk_bf16_f32 v13, v8, v13
	global_store_dword v1, v10, s[14:15]
	s_add_i32 s0, s60, s2
	s_cmp_lt_i32 s0, 0x18000
	s_cbranch_scc0 .Lckv_skip1
	global_store_dword v1, v11, s[22:23]
.Lckv_skip1:
	v_readlane_b32 s0, v253, 49
	s_add_i32 s0, s0, s2
	s_cmp_lt_i32 s0, 0x18000
	s_cbranch_scc0 .Lckv_skip2
	global_store_dword v1, v12, s[24:25]
.Lckv_skip2:
	v_readlane_b32 s0, v254, 36
	s_add_i32 s0, s0, s2
	s_cmp_lt_i32 s0, 0x18000
	s_cbranch_scc0 .Lckv_skip3
	global_store_dword v1, v13, s[10:11]
.Lckv_skip3:
	s_branch .LBB0_191
